# RWKV prep: decay computed as exp(-e^-0.5 * sigmoid(z)) (identity for exp(-exp(-softplus(-z)-0.5))), 16 fewer VALU per channel; hazards re-checked with a wait-state checker
# baseline (speedup 1.0000x reference)
; __device__ __forceinline__ void rwkv_block(KP p, int o, int b, int hd, LAS unsigned char* lds, const bf16_t* P, bf16_t* YB) {
;     ...
;             cv = unpack4(d.r[1]); pv = unpack4(d.r[0]); const f32x4 rr = cv + mu_r * (pv - cv);
;             cv = unpack4(d.k[1]); pv = unpack4(d.k[0]); const f32x4 k0 = cv + mu_k * (pv - cv);
;             cv = unpack4(d.v[1]); pv = unpack4(d.v[0]); const f32x4 vv = cv + mu_v * (pv - cv);
;             {
;                 f32x4 la, lb;
;                 cv = unpack4((u32x2){d.l[1].x, d.l[1].y}); pv = unpack4((u32x2){d.l[0].x, d.l[0].y}); la = cv + mu_la * (pv - cv);
;                 cv = unpack4((u32x2){d.l[1].z, d.l[1].w}); pv = unpack4((u32x2){d.l[0].z, d.l[0].w}); lb = cv + mu_lb * (pv - cv);
;                 float o8[8];
; #pragma unroll
;                 for (int i = 0; i < 4; ++i) {
;                     const float sa = sigmoidf_(lsc * la[i]), sb = sigmoidf_(lsc * lb[i]);
;                     o8[i] = jg < 4 ? 2.0f * sa - 1.0f : (jg < 8 ? la[i] : sa);
;                     o8[4 + i] = jg < 4 ? 2.0f * sb - 1.0f : (jg < 8 ? lb[i] : sb);
;                 }
;                 u32x4 w; w.x = pk2(o8[0], o8[1]); w.y = pk2(o8[2], o8[3]); w.z = pk2(o8[4], o8[5]); w.w = pk2(o8[6], o8[7]);
;                 *(LAS u32x4*)(Lin + t4 * 136 + 8 * jg) = w;
;             }
;             LDS_WAIT(); asm volatile("" ::: "memory");
; #pragma unroll
;             for (int ct = 0; ct < 4; ++ct) {
;                 f32x4 c0 = {0.f, 0.f, 0.f, 0.f}, c1 = {0.f, 0.f, 0.f, 0.f}, c2 = {0.f, 0.f, 0.f, 0.f};
;                 c0 = mfma16(*(const LAS bf16x8*)(Lin + fr * 136 + fq * 8), *(const LAS bf16x8*)(wBt + (ct * 16 + fr) * 40 + fq * 8), c0);
;                 c1 = mfma16(*(const LAS bf16x8*)(Lin + fr * 136 + 32 + fq * 8), *(const LAS bf16x8*)(aBt + (ct * 16 + fr) * 40 + fq * 8), c1);
; #pragma unroll
;                 for (int kb = 0; kb < 2; ++kb)
;                     c2 = mfma16(*(const LAS bf16x8*)(Lin + fr * 136 + 64 + kb * 32 + fq * 8), *(const LAS bf16x8*)(gBt + (ct * 16 + fr) * 72 + kb * 32 + fq * 8), c2);
;                 if (fq == 0) {
; #pragma unroll
;                     for (int jj = 0; jj < 4; ++jj) { Lout[jj * 68 + ct * 16 + fr] = c0[jj]; Lout[272 + jj * 68 + ct * 16 + fr] = c1[jj]; Lout[544 + jj * 68 + ct * 16 + fr] = c2[jj]; }
;                 }
;             }
;             LDS_WAIT(); asm volatile("" ::: "memory");
.LBB0_199:
	s_or_b64 exec, exec, s[16:17]
	v_lshlrev_b32_e32 v80, 16, v104
	v_lshlrev_b32_e32 v3, 16, v114
	v_sub_f32_e32 v84, v3, v80
	v_mul_u32_u24_e32 v3, 0x44, v131
	s_waitcnt lgkmcnt(0)
	v_lshlrev_b32_e32 v72, 2, v3
	v_lshlrev_b32_e32 v3, 2, v156
	v_add3_u32 v141, v128, v72, v3
	ds_read_b128 v[72:75], v141 offset:36864
	v_and_b32_e32 v81, 0xffff0000, v104
	v_lshlrev_b32_e32 v82, 16, v105
	v_and_b32_e32 v68, 0xffff0000, v114
	v_lshlrev_b32_e32 v69, 16, v115
	v_sub_f32_e32 v85, v68, v81
	v_sub_f32_e32 v86, v69, v82
	v_lshlrev_b32_e32 v68, 16, v108
	v_and_b32_e32 v69, 0xffff0000, v108
	v_and_b32_e32 v71, 0xffff0000, v109
	v_lshlrev_b32_e32 v76, 16, v110
	v_and_b32_e32 v77, 0xffff0000, v110
	v_and_b32_e32 v78, 0xffff0000, v111
	v_sub_f32_e32 v93, v77, v69
	v_sub_f32_e32 v92, v76, v68
	v_sub_f32_e32 v95, v78, v71
	ds_read_b128 v[76:79], v141 offset:37952
	s_waitcnt lgkmcnt(1)
	v_add_f32_e32 v72, v32, v72
	v_mul_f32_e64 v128, v72, s68
	v_exp_f32_e32 v145, v128
	v_lshlrev_b32_e32 v88, 16, v106
	v_lshlrev_b32_e32 v97, 16, v112
	v_sub_f32_e32 v128, v97, v88
	v_add_f32_e32 v97, 1.0, v145
	v_lshlrev_b32_e32 v90, 16, v107
	v_and_b32_e32 v91, 0xffff0000, v107
	v_rcp_f32_e32 v72, v97
	v_lshlrev_b32_e32 v143, 16, v113
	v_and_b32_e32 v144, 0xffff0000, v113
	v_sub_f32_e32 v145, v144, v91
	v_sub_f32_e32 v144, v143, v90
	v_add_f32_e32 v73, v33, v73
	v_mul_f32_e64 v97, v73, s68
	v_exp_f32_e32 v97, v97
	s_waitcnt lgkmcnt(0)
	v_add_f32_e32 v76, v36, v76
	v_mul_f32_e32 v76, 0xbfb8aa3b, v76
	v_add_f32_e32 v77, v37, v77
	v_add_f32_e32 v97, 1.0, v97
	v_exp_f32_e32 v76, v76
	v_rcp_f32_e32 v73, v97
	v_mul_f32_e32 v77, 0xbfb8aa3b, v77
	v_add_f32_e32 v74, v34, v74
	v_exp_f32_e32 v77, v77
	v_add_f32_e32 v76, 1.0, v76
	v_rcp_f32_e32 v148, v76
	v_mul_f32_e64 v97, v74, s68
	v_exp_f32_e32 v97, v97
	v_add_f32_e32 v76, 1.0, v77
	v_and_b32_e32 v89, 0xffff0000, v106
	v_and_b32_e32 v129, 0xffff0000, v112
	v_rcp_f32_e32 v149, v76
	v_add_f32_e32 v97, 1.0, v97
	v_sub_f32_e32 v129, v129, v89
	v_pk_fma_f32 v[88:89], v[8:9], v[128:129], v[88:89]
	v_pk_add_f32 v[76:77], v[148:149], -1.0 op_sel_hi:[1,0]
	v_rcp_f32_e32 v74, v97
	v_pk_fma_f32 v[76:77], v[44:45], v[76:77], 1.0 op_sel_hi:[1,1,0]
	v_pk_fma_f32 v[80:81], v[4:5], v[84:85], v[80:81]
	v_pk_mul_f32 v[76:77], v[88:89], v[76:77]
	v_mul_f32_e32 v128, v80, v76
	v_fma_f32 v143, v48, v128, 0
	v_pk_mul_f32 v[128:129], v[40:41], v[88:89]
	v_mul_f32_e32 v97, v81, v77
	v_add_f32_e32 v75, v35, v75
	v_fmac_f32_e32 v143, v49, v97
	v_mul_f32_e64 v97, v75, s68
	v_exp_f32_e32 v97, v97
	v_add_f32_e32 v78, v38, v78
	v_mul_f32_e32 v78, 0xbfb8aa3b, v78
	v_add_f32_e32 v97, 1.0, v97
	v_add_f32_e32 v79, v39, v79
	v_exp_f32_e32 v78, v78
	v_rcp_f32_e32 v75, v97
	v_mul_f32_e32 v79, 0xbfb8aa3b, v79
	v_exp_f32_e32 v79, v79
	v_add_f32_e32 v78, 1.0, v78
	v_rcp_f32_e32 v146, v78
	v_add_f32_e32 v78, 1.0, v79
	v_rcp_f32_e32 v147, v78
	v_pk_fma_f32 v[90:91], v[10:11], v[144:145], v[90:91]
	v_pk_mul_f32 v[88:89], v[128:129], v[128:129]
	v_pk_add_f32 v[78:79], v[146:147], -1.0 op_sel_hi:[1,0]
	v_pk_mul_f32 v[144:145], v[42:43], v[90:91]
	v_pk_fma_f32 v[78:79], v[46:47], v[78:79], 1.0 op_sel_hi:[1,1,0]
	v_add_f32_e32 v88, v88, v89
	v_pk_mul_f32 v[78:79], v[90:91], v[78:79]
	v_pk_mul_f32 v[90:91], v[144:145], v[144:145]
	v_and_b32_e32 v83, 0xffff0000, v105
	v_add_f32_e32 v88, v90, v88
	v_add_f32_e32 v88, v91, v88
	v_and_b32_e32 v70, 0xffff0000, v115
	v_sub_f32_e32 v87, v70, v83
	v_add_f32_dpp v88, v88, v88 quad_perm:[1,0,3,2] row_mask:0xf bank_mask:0xf bound_ctrl:1
	v_pk_fma_f32 v[82:83], v[6:7], v[86:87], v[82:83]
	s_nop 0
	v_add_f32_dpp v88, v88, v88 quad_perm:[2,3,0,1] row_mask:0xf bank_mask:0xf bound_ctrl:1
	v_mul_f32_e32 v97, v82, v78
	s_nop 0
	v_add_f32_dpp v88, v88, v88 row_half_mirror row_mask:0xf bank_mask:0xf bound_ctrl:1
	v_fmac_f32_e32 v143, v50, v97
	s_nop 0
	v_add_f32_dpp v88, v88, v88 row_mirror row_mask:0xf bank_mask:0xf bound_ctrl:1
	v_sqrt_f32_e32 v97, v88
	v_mul_f32_e32 v89, v83, v79
	v_fmac_f32_e32 v143, v51, v89
	v_pk_fma_f32 v[88:89], v[24:25], v[92:93], v[68:69]
	v_xor_b32_e32 v68, 0x80000000, v97
	v_min_f32_e32 v68, 0xab8cbccc, v68
	v_rcp_f32_e32 v68, v68
	v_lshlrev_b32_e32 v70, 16, v109
	v_lshlrev_b32_e32 v94, 16, v111
	v_mul_f32_e32 v72, 0xbf60028b, v72
	v_mul_f32_e32 v73, 0xbf60028b, v73
	v_mul_f32_e32 v74, 0xbf60028b, v74
	v_mul_f32_e32 v75, 0xbf60028b, v75
	v_add_f32_dpp v69, v143, v143 quad_perm:[1,0,3,2] row_mask:0xf bank_mask:0xf bound_ctrl:1
	v_sub_f32_e32 v94, v94, v70
	v_exp_f32_e32 v72, v72
	v_exp_f32_e32 v73, v73
	v_exp_f32_e32 v74, v74
	v_exp_f32_e32 v75, v75
	v_add_f32_dpp v69, v69, v69 quad_perm:[2,3,0,1] row_mask:0xf bank_mask:0xf bound_ctrl:1
	v_pk_fma_f32 v[90:91], v[26:27], v[94:95], v[70:71]
	v_lshlrev_b32_e32 v71, 8, v98
	v_add_f32_dpp v69, v69, v69 row_half_mirror row_mask:0xf bank_mask:0xf bound_ctrl:1
	ds_read_b128 v[84:87], v141 offset:39040
	v_pk_mul_f32 v[94:95], v[144:145], v[68:69] op_sel_hi:[1,0]
	v_pk_mul_f32 v[92:93], v[128:129], v[68:69] op_sel_hi:[1,0]
	v_add_u32_e32 v68, 0, v71
	v_readlane_b32 s1, v255, 12
	v_pk_mul_f32 v[144:145], v[148:149], v[92:93] neg_lo:[0,1] neg_hi:[0,1]
	v_add_u32_e32 v143, v68, v102
	v_add_u32_e32 v68, s1, v71
	v_readlane_b32 s1, v255, 13
	v_pk_mul_f32 v[146:147], v[146:147], v[94:95] neg_lo:[0,1] neg_hi:[0,1]
	ds_write_b128 v143, v[72:75] offset:49920
	ds_write_b128 v143, v[92:95] offset:54016
	ds_write_b128 v143, v[144:147] offset:58112
	ds_write_b128 v143, v[76:79] offset:62208
	v_add_u32_e32 v144, v68, v102
	v_add_u32_e32 v68, s1, v71
	v_readlane_b32 s1, v255, 14
	v_mov_b32_dpp v70, v69 row_mirror row_mask:0xf bank_mask:0xf bound_ctrl:1
	v_add_u32_e32 v146, v68, v102
	v_add_u32_e32 v71, s1, v71
	v_add_u32_e32 v148, v71, v102
	v_cmp_eq_u32_e64 s[16:17], 0, v142
	ds_write_b128 v144, v[80:83]
	ds_write_b128 v146, v[88:91]
	s_waitcnt lgkmcnt(6)
	ds_write_b128 v148, v[84:87]
	s_and_saveexec_b64 s[18:19], s[16:17]
	v_lshl_add_u32 v72, v98, 2, 0
	v_add_u32_e32 v72, 0x14300, v72
	v_add_f32_e32 v69, v69, v70
	ds_write_b32 v72, v69
	s_or_b64 exec, exec, s[18:19]
	v_lshlrev_b32_e32 v69, 6, v98
	v_lshlrev_b32_e32 v69, 2, v69
	v_readlane_b32 s1, v255, 15
	v_lshlrev_b32_e32 v73, 2, v98
	s_waitcnt lgkmcnt(0)
	v_add_u32_e32 v153, v68, v3
	v_add_u32_e32 v149, s1, v69
	v_readlane_b32 s1, v255, 16
	s_lshl_b64 s[18:19], s[24:25], 23
	v_mul_u32_u24_e32 v70, 0x50, v142
	v_add_u32_e32 v145, s1, v73
	v_readlane_b32 s1, v255, 17
	v_mul_u32_u24_e32 v72, 0x90, v142
	s_waitcnt lgkmcnt(0)
	s_barrier
; #define LAS __attribute__((address_space(3)))
; __device__ __forceinline__ unsigned pk2(float lo, float hi) { const f32x2 v = {lo, hi}; const bf16x2n b = __builtin_convertvector(v, bf16x2n); return __builtin_bit_cast(unsigned, b); }
; #define LDS_WAIT() asm volatile("s_waitcnt lgkmcnt(0)" ::: "memory")
; #define LDS_BAR() do { asm volatile("s_waitcnt lgkmcnt(0)" ::: "memory"); __builtin_amdgcn_s_barrier(); asm volatile("" ::: "memory"); } while (0)
; __device__ __forceinline__ void rwkv_block(KP p, int o, int b, int hd, LAS unsigned char* lds, const bf16_t* P, bf16_t* YB) {
;     ...
;         auto outp = [&](int m) {
;             LAS float* B = (LAS float*)(lds + BUF0 + (m & 1) * BUFSZ);
;             LAS float* Vv = B + 5120; LAS float* Gg = B + 6144; LAS float* Yy = B + 7168; LAS float* Bon = B + 8192;
;             const int tt = 4 * q + t4; const size_t row = rbase + m * 16 + tt;
;             const f32x4 y = *(const LAS f32x4*)(Yy + tt * 64 + 4 * jg);
;             const float mean = red16((y.x + y.y) + (y.z + y.w)) * (1.f / 64.f);
;             const f32x4 dd = y - mean;
;             const float var = red16((dd.x * dd.x + dd.y * dd.y) + (dd.z * dd.z + dd.w * dd.w)) * (1.f / 64.f);
;             const f32x4 yn = dd * __builtin_amdgcn_rsqf(var + 64e-5f) * lng + lnb;
;             const f32x4 ov = (yn + Bon[tt] * *(const LAS f32x4*)(Vv + tt * 64 + 4 * jg)) * *(const LAS f32x4*)(Gg + tt * 64 + 4 * jg);
;             u32x2 w; w.x = pk2(ov.x, ov.y); w.y = pk2(ov.z, ov.w);
;             *(u32x2*)(YB + row * DM + ch0) = w;
;             LDS_WAIT(); asm volatile("" ::: "memory");
;         };
;         Raw rawA, rawB;
;         load_rows(0, rawA);
;         load_rows(1, rawB);
;         prep(0, rawA);
;         LDS_BAR();
; #pragma unroll 1
;         for (int n = 0; n < 256; n += 2) {
;             if (n + 2 < 256) load_rows(n + 2, rawA);
;             if (n >= 1) outp(n - 1);
;             prep(n + 1, rawB);
;             LDS_BAR();
;             if (n + 3 < 256) load_rows(n + 3, rawB);
;             outp(n);
;             if (n + 2 < 256) prep(n + 2, rawA);
;             LDS_BAR();
;         }
	v_add_u32_e32 v150, s1, v69
	v_readlane_b32 s1, v255, 18
	v_add_u32_e32 v147, v150, v3
	v_add_u32_e32 v154, v71, v3
	v_add_u32_e32 v151, s1, v69
	v_readlane_b32 s1, v255, 19
	v_add_u32_e32 v142, v151, v3
	v_lshlrev_b32_e32 v3, 1, v156
	v_add_u32_e32 v74, s1, v69
	v_readlane_b32 s1, v255, 20
	v_mov_b32_e32 v97, v1
	v_lshl_add_u64 v[128:129], s[92:93], 0, v[96:97]
	v_add_u32_e32 v75, s1, v69
	v_readlane_b32 s1, v255, 21
	v_lshl_or_b32 v155, v130, 2, v131
	s_mov_b32 s56, -16
	v_add_u32_e32 v76, s1, v69
	v_readlane_b32 s1, v255, 22
	v_add_u32_e32 v156, v74, v102
	v_add_u32_e32 v157, v75, v102
	v_add_u32_e32 v77, s1, v69
	v_readlane_b32 s1, v255, 23
	v_add_u32_e32 v158, v76, v102
	v_add_u32_e32 v159, v77, v102
	v_add_u32_e32 v78, s1, v69
	v_readlane_b32 s1, v255, 24
	v_add_u32_e32 v160, v78, v102
	v_add_u32_e32 v162, v0, v70
	v_add_u32_e32 v79, s1, v69
	s_add_i32 s1, 0, 0x14300
	v_add_u32_e32 v152, s1, v73
	v_lshlrev_b64 v[68:69], 11, v[98:99]
	s_lshl_b32 s1, s72, 1
	v_lshl_add_u64 v[68:69], s[18:19], 0, v[68:69]
	s_and_b32 s1, s1, 0x380
	v_or3_b32 v68, s1, v3, v68
	v_lshl_add_u64 v[130:131], s[92:93], 0, v[68:69]
	s_mov_b32 s1, 0
	v_add_u32_e32 v161, v79, v102
	v_add_u32_e32 v163, v0, v72
	s_branch .LBB0_204

; #define LAS __attribute__((address_space(3)))
; __device__ __forceinline__ float rcp_(float x) { return __builtin_amdgcn_rcpf(x); }
; __device__ __forceinline__ float sigmoidf_(float x) { return rcp_(1.0f + __expf(-x)); }
; __device__ __forceinline__ float softplus_fast(float x) { return fmaxf(x, 0.f) + __logf(1.0f + __expf(-fabsf(x))); }
; #define LDS_BAR() do { asm volatile("s_waitcnt lgkmcnt(0)" ::: "memory"); __builtin_amdgcn_s_barrier(); asm volatile("" ::: "memory"); } while (0)
; __device__ __forceinline__ void rwkv_block(KP p, int o, int b, int hd, LAS unsigned char* lds, const bf16_t* P, bf16_t* YB) {
;     ...
;             const f32x4 wl = *(const LAS f32x4*)(Lout + t4 * 68 + 4 * jg), al = *(const LAS f32x4*)(Lout + 272 + t4 * 68 + 4 * jg), gg = *(const LAS f32x4*)(Lout + 544 + t4 * 68 + 4 * jg);
;             f32x4 decay, kk, bbv, km;
;             float nsq = 0.f, bon = 0.f;
; #pragma unroll
;             for (int i = 0; i < 4; ++i) {
;                 const float w_raw = -softplus_fast(-(w0[i] + wl[i])) - 0.5f;
;                 decay[i] = __expf(-__expf(w_raw));
;                 const float a = sigmoidf_(a0[i] + al[i]);
;                 kk[i] = k0[i] * k_k[i];
;                 nsq += kk[i] * kk[i];
;                 km[i] = k0[i] * (1.0f + (a - 1.0f) * k_a[i]);
;                 bon += rr[i] * km[i] * r_k[i];
;                 bbv[i] = a;
;             }
;             nsq = red16(nsq); bon = red16(bon);
;             const float inv = rcp_(fmaxf(__builtin_amdgcn_sqrtf(nsq), 1e-12f));
;             kk = kk * inv; bbv = bbv * kk;
;             *(LAS f32x4*)(Wd + tt * 64 + 4 * jg) = decay; *(LAS f32x4*)(KK + tt * 64 + 4 * jg) = -kk; *(LAS f32x4*)(BB + tt * 64 + 4 * jg) = bbv; *(LAS f32x4*)(KM + tt * 64 + 4 * jg) = km;
;             *(LAS f32x4*)(Rr + tt * 64 + 4 * jg) = rr; *(LAS f32x4*)(Vv + tt * 64 + 4 * jg) = vv; *(LAS f32x4*)(Gg + tt * 64 + 4 * jg) = gg;
;             if (jg == 0) Bon[tt] = bon;
;     ...
;             LDS_BAR();
;             if (n + 3 < 256) load_rows(n + 3, rawB);
.LBB0_216:
	s_or_b64 exec, exec, s[18:19]
	s_waitcnt lgkmcnt(0)
	v_lshlrev_b32_e32 v78, 16, v121
	v_and_b32_e32 v79, 0xffff0000, v121
	s_nop 2
	v_lshlrev_b32_e32 v68, 16, v123
	v_and_b32_e32 v69, 0xffff0000, v123
	v_sub_f32_e32 v83, v69, v79
	v_sub_f32_e32 v82, v68, v78
	ds_read_b128 v[68:71], v141 offset:36864
	v_lshlrev_b32_e32 v88, 16, v116
	v_and_b32_e32 v89, 0xffff0000, v116
	v_and_b32_e32 v91, 0xffff0000, v117
	v_lshlrev_b32_e32 v72, 16, v126
	v_and_b32_e32 v73, 0xffff0000, v126
	v_and_b32_e32 v74, 0xffff0000, v127
	v_sub_f32_e32 v93, v73, v89
	v_sub_f32_e32 v92, v72, v88
	v_sub_f32_e32 v95, v74, v91
	ds_read_b128 v[72:75], v141 offset:37952
	s_waitcnt lgkmcnt(1)
	v_add_f32_e32 v68, v32, v68
	v_mul_f32_e64 v164, v68, s68
	v_exp_f32_e32 v167, v164
	v_lshlrev_b32_e32 v76, 16, v120
	v_lshlrev_b32_e32 v0, 16, v122
	v_sub_f32_e32 v80, v0, v76
	v_lshlrev_b32_e32 v84, 16, v118
	v_lshlrev_b32_e32 v0, 16, v124
	v_and_b32_e32 v77, 0xffff0000, v120
	v_and_b32_e32 v3, 0xffff0000, v122
	v_sub_f32_e32 v164, v0, v84
	v_add_f32_e32 v0, 1.0, v167
	v_sub_f32_e32 v81, v3, v77
	v_and_b32_e32 v85, 0xffff0000, v118
	v_and_b32_e32 v3, 0xffff0000, v124
	v_sub_f32_e32 v165, v3, v85
	v_lshlrev_b32_e32 v86, 16, v119
	v_rcp_f32_e32 v0, v0
	v_and_b32_e32 v87, 0xffff0000, v119
	v_lshlrev_b32_e32 v97, 16, v125
	v_and_b32_e32 v166, 0xffff0000, v125
	v_sub_f32_e32 v167, v166, v87
	v_add_f32_e32 v3, v33, v69
	v_mul_f32_e64 v68, v3, s68
	v_exp_f32_e32 v68, v68
	s_waitcnt lgkmcnt(0)
	v_add_f32_e32 v69, v36, v72
	v_add_f32_e32 v68, 1.0, v68
	v_mul_f32_e32 v69, 0xbfb8aa3b, v69
	v_exp_f32_e32 v69, v69
	v_rcp_f32_e32 v3, v68
	v_mul_f32_e32 v0, 0xbf60028b, v0
	v_exp_f32_e32 v68, v0
	v_add_f32_e32 v0, 1.0, v69
	v_rcp_f32_e32 v168, v0
	v_add_f32_e32 v69, v37, v73
	v_mul_f32_e32 v69, 0xbfb8aa3b, v69
	v_exp_f32_e32 v69, v69
	v_sub_f32_e32 v166, v97, v86
	v_add_f32_e32 v0, 1.0, v69
	v_rcp_f32_e32 v169, v0
	v_mul_f32_e32 v0, 0xbf60028b, v3
	v_exp_f32_e32 v69, v0
	v_add_f32_e32 v0, v34, v70
	v_mul_f32_e64 v3, v0, s68
	v_exp_f32_e32 v3, v3
	v_pk_add_f32 v[72:73], v[168:169], -1.0 op_sel_hi:[1,0]
	v_pk_fma_f32 v[84:85], v[8:9], v[164:165], v[84:85]
	v_pk_fma_f32 v[72:73], v[44:45], v[72:73], 1.0 op_sel_hi:[1,1,0]
	v_add_f32_e32 v3, 1.0, v3
	v_pk_fma_f32 v[76:77], v[4:5], v[80:81], v[76:77]
	v_pk_mul_f32 v[72:73], v[84:85], v[72:73]
	v_rcp_f32_e32 v0, v3
	v_mul_f32_e32 v70, v76, v72
	v_fma_f32 v97, v48, v70, 0
	v_pk_fma_f32 v[86:87], v[10:11], v[166:167], v[86:87]
	v_pk_fma_f32 v[78:79], v[6:7], v[82:83], v[78:79]
	v_mul_f32_e32 v3, v77, v73
	v_fmac_f32_e32 v97, v49, v3
	v_add_f32_e32 v3, v35, v71
	v_mul_f32_e64 v70, v3, s68
	v_exp_f32_e32 v70, v70
	v_add_f32_e32 v71, v38, v74
	v_add_f32_e32 v70, 1.0, v70
	v_mul_f32_e32 v71, 0xbfb8aa3b, v71
	v_exp_f32_e32 v71, v71
	v_rcp_f32_e32 v3, v70
	v_mul_f32_e32 v0, 0xbf60028b, v0
	v_exp_f32_e32 v70, v0
	v_add_f32_e32 v0, 1.0, v71
	v_rcp_f32_e32 v170, v0
	v_add_f32_e32 v71, v39, v75
	v_mul_f32_e32 v71, 0xbfb8aa3b, v71
	v_exp_f32_e32 v71, v71
	s_nop 0
	v_add_f32_e32 v0, 1.0, v71
	v_rcp_f32_e32 v171, v0
	v_pk_mul_f32 v[164:165], v[40:41], v[84:85]
	v_mul_f32_e32 v0, 0xbf60028b, v3
	v_pk_mul_f32 v[84:85], v[164:165], v[164:165]
	v_pk_add_f32 v[74:75], v[170:171], -1.0 op_sel_hi:[1,0]
	v_exp_f32_e32 v71, v0
	v_pk_fma_f32 v[74:75], v[46:47], v[74:75], 1.0 op_sel_hi:[1,1,0]
	v_pk_mul_f32 v[166:167], v[42:43], v[86:87]
	v_pk_mul_f32 v[74:75], v[86:87], v[74:75]
	v_pk_mul_f32 v[86:87], v[166:167], v[166:167]
	v_mul_f32_e32 v0, v78, v74
	v_fmac_f32_e32 v97, v50, v0
	v_add_f32_e32 v0, v84, v85
	v_add_f32_e32 v0, v86, v0
	v_add_f32_e32 v0, v87, v0
	v_pk_fma_f32 v[84:85], v[24:25], v[92:93], v[88:89]
	v_mul_f32_e32 v3, v79, v75
	v_add_f32_dpp v0, v0, v0 quad_perm:[1,0,3,2] row_mask:0xf bank_mask:0xf bound_ctrl:1
	v_lshlrev_b32_e32 v90, 16, v117
	v_lshlrev_b32_e32 v94, 16, v127
	v_add_f32_dpp v0, v0, v0 quad_perm:[2,3,0,1] row_mask:0xf bank_mask:0xf bound_ctrl:1
	ds_read_b128 v[80:83], v141 offset:39040
	v_fmac_f32_e32 v97, v51, v3
	v_add_f32_dpp v0, v0, v0 row_half_mirror row_mask:0xf bank_mask:0xf bound_ctrl:1
	v_sub_f32_e32 v94, v94, v90
	v_add_f32_dpp v3, v97, v97 quad_perm:[1,0,3,2] row_mask:0xf bank_mask:0xf bound_ctrl:1
	v_add_f32_dpp v0, v0, v0 row_mirror row_mask:0xf bank_mask:0xf bound_ctrl:1
	v_sqrt_f32_e32 v0, v0
	v_pk_fma_f32 v[86:87], v[26:27], v[94:95], v[90:91]
	v_xor_b32_e32 v0, 0x80000000, v0
	v_min_f32_e32 v0, 0xab8cbccc, v0
	v_rcp_f32_e32 v88, v0
	s_nop 0
	v_add_f32_dpp v0, v3, v3 quad_perm:[2,3,0,1] row_mask:0xf bank_mask:0xf bound_ctrl:1
	v_pk_mul_f32 v[90:91], v[166:167], v[88:89] op_sel_hi:[1,0]
	v_pk_mul_f32 v[88:89], v[164:165], v[88:89] op_sel_hi:[1,0]
	v_add_f32_dpp v0, v0, v0 row_half_mirror row_mask:0xf bank_mask:0xf bound_ctrl:1
	v_pk_mul_f32 v[94:95], v[170:171], v[90:91] neg_lo:[0,1] neg_hi:[0,1]
	v_pk_mul_f32 v[92:93], v[168:169], v[88:89] neg_lo:[0,1] neg_hi:[0,1]
	ds_write_b128 v156, v[68:71]
	ds_write_b128 v157, v[88:91]
	ds_write_b128 v158, v[92:95]
	ds_write_b128 v159, v[72:75]
	ds_write_b128 v160, v[76:79]
	v_add_u32_e32 v68, v150, v102
	v_mov_b32_dpp v3, v0 row_mirror row_mask:0xf bank_mask:0xf bound_ctrl:1
	ds_write_b128 v68, v[84:87]
	v_add_u32_e32 v68, v151, v102
	s_waitcnt lgkmcnt(6)
	ds_write_b128 v68, v[80:83]
	s_and_saveexec_b64 s[18:19], s[16:17]
	v_add_f32_e32 v0, v0, v3
	ds_write_b32 v145, v0
	s_or_b64 exec, exec, s[18:19]
	s_waitcnt lgkmcnt(0)
	s_waitcnt lgkmcnt(0)
	s_barrier
	s_cmpk_gt_u32 s1, 0xfc
	s_cbranch_scc1 .LBB0_220
	v_add3_u32 v0, v155, s56, 48
	v_lshl_add_u64 v[60:61], s[22:23], 0, v[0:1]
	v_mov_b64_e32 v[62:63], s[94:95]
	v_mad_u64_u32 v[62:63], s[18:19], v60, s81, v[62:63]
	v_mad_i32_i24 v63, v61, s81, v63
	v_mov_b32_e32 v97, v1
	v_mov_b32_e32 v3, v1
	v_lshl_add_u64 v[60:61], v[62:63], 0, v[96:97]
	v_lshl_add_u64 v[64:65], v[62:63], 0, v[2:3]
	v_add_co_u32_e32 v62, vcc, 0xfffff000, v60
	s_nop 1
	v_addc_co_u32_e32 v63, vcc, -1, v61, vcc
	global_load_dwordx2 v[116:117], v[60:61], off offset:2048
	global_load_dwordx2 v[122:123], v[62:63], off offset:-2560
	global_load_dwordx2 v[118:119], v[60:61], off offset:1024
	global_load_dwordx2 v[120:121], v[60:61], off
	global_load_dwordx2 v[124:125], v[62:63], off offset:-1536
	global_load_dwordx2 v[126:127], v[62:63], off offset:-512
	s_nop 0
	global_load_dwordx4 v[60:63], v[64:65], off offset:3072
	s_nop 0
	global_load_dwordx4 v[64:67], v[64:65], off offset:-3584

; #define LAS __attribute__((address_space(3)))
; __device__ __forceinline__ float rcp_(float x) { return __builtin_amdgcn_rcpf(x); }
; __device__ __forceinline__ float sigmoidf_(float x) { return rcp_(1.0f + __expf(-x)); }
; __device__ __forceinline__ float softplus_fast(float x) { return fmaxf(x, 0.f) + __logf(1.0f + __expf(-fabsf(x))); }
; __device__ __forceinline__ void rwkv_block(KP p, int o, int b, int hd, LAS unsigned char* lds, const bf16_t* P, bf16_t* YB) {
;     ...
;             const f32x4 wl = *(const LAS f32x4*)(Lout + t4 * 68 + 4 * jg), al = *(const LAS f32x4*)(Lout + 272 + t4 * 68 + 4 * jg), gg = *(const LAS f32x4*)(Lout + 544 + t4 * 68 + 4 * jg);
;             f32x4 decay, kk, bbv, km;
;             float nsq = 0.f, bon = 0.f;
; #pragma unroll
;             for (int i = 0; i < 4; ++i) {
;                 const float w_raw = -softplus_fast(-(w0[i] + wl[i])) - 0.5f;
;                 decay[i] = __expf(-__expf(w_raw));
;                 const float a = sigmoidf_(a0[i] + al[i]);
;                 kk[i] = k0[i] * k_k[i];
;                 nsq += kk[i] * kk[i];
;                 km[i] = k0[i] * (1.0f + (a - 1.0f) * k_a[i]);
;                 bon += rr[i] * km[i] * r_k[i];
;                 bbv[i] = a;
;             }
;             nsq = red16(nsq); bon = red16(bon);
;             const float inv = rcp_(fmaxf(__builtin_amdgcn_sqrtf(nsq), 1e-12f));
;             kk = kk * inv; bbv = bbv * kk;
;             *(LAS f32x4*)(Wd + tt * 64 + 4 * jg) = decay; *(LAS f32x4*)(KK + tt * 64 + 4 * jg) = -kk; *(LAS f32x4*)(BB + tt * 64 + 4 * jg) = bbv; *(LAS f32x4*)(KM + tt * 64 + 4 * jg) = km;
;             *(LAS f32x4*)(Rr + tt * 64 + 4 * jg) = rr; *(LAS f32x4*)(Vv + tt * 64 + 4 * jg) = vv; *(LAS f32x4*)(Gg + tt * 64 + 4 * jg) = gg;
;             if (jg == 0) Bon[tt] = bon;
.LBB0_229:
	s_or_b64 exec, exec, s[18:19]
	s_waitcnt lgkmcnt(0)
	v_lshlrev_b32_e32 v78, 16, v105
	v_and_b32_e32 v79, 0xffff0000, v105
	s_nop 2
	v_lshlrev_b32_e32 v68, 16, v115
	v_and_b32_e32 v69, 0xffff0000, v115
	v_sub_f32_e32 v83, v69, v79
	v_sub_f32_e32 v82, v68, v78
	ds_read_b128 v[68:71], v141 offset:36864
	v_lshlrev_b32_e32 v88, 16, v108
	v_and_b32_e32 v89, 0xffff0000, v108
	v_and_b32_e32 v91, 0xffff0000, v109
	v_lshlrev_b32_e32 v72, 16, v110
	v_and_b32_e32 v73, 0xffff0000, v110
	v_and_b32_e32 v74, 0xffff0000, v111
	v_sub_f32_e32 v93, v73, v89
	v_sub_f32_e32 v92, v72, v88
	v_sub_f32_e32 v95, v74, v91
	ds_read_b128 v[72:75], v141 offset:37952
	s_waitcnt lgkmcnt(1)
	v_add_f32_e32 v68, v32, v68
	v_mul_f32_e64 v164, v68, s68
	v_exp_f32_e32 v167, v164
	v_lshlrev_b32_e32 v76, 16, v104
	v_lshlrev_b32_e32 v0, 16, v114
	v_sub_f32_e32 v80, v0, v76
	v_lshlrev_b32_e32 v84, 16, v106
	v_lshlrev_b32_e32 v0, 16, v112
	v_and_b32_e32 v77, 0xffff0000, v104
	v_and_b32_e32 v3, 0xffff0000, v114
	v_sub_f32_e32 v164, v0, v84
	v_add_f32_e32 v0, 1.0, v167
	v_sub_f32_e32 v81, v3, v77
	v_and_b32_e32 v85, 0xffff0000, v106
	v_and_b32_e32 v3, 0xffff0000, v112
	v_sub_f32_e32 v165, v3, v85
	v_lshlrev_b32_e32 v86, 16, v107
	v_rcp_f32_e32 v0, v0
	v_and_b32_e32 v87, 0xffff0000, v107
	v_lshlrev_b32_e32 v97, 16, v113
	v_and_b32_e32 v166, 0xffff0000, v113
	v_sub_f32_e32 v167, v166, v87
	v_add_f32_e32 v3, v33, v69
	v_mul_f32_e64 v68, v3, s68
	v_exp_f32_e32 v68, v68
	s_waitcnt lgkmcnt(0)
	v_add_f32_e32 v69, v36, v72
	v_add_f32_e32 v68, 1.0, v68
	v_mul_f32_e32 v69, 0xbfb8aa3b, v69
	v_exp_f32_e32 v69, v69
	v_rcp_f32_e32 v3, v68
	v_mul_f32_e32 v0, 0xbf60028b, v0
	v_exp_f32_e32 v68, v0
	v_add_f32_e32 v0, 1.0, v69
	v_rcp_f32_e32 v168, v0
	v_add_f32_e32 v69, v37, v73
	v_mul_f32_e32 v69, 0xbfb8aa3b, v69
	v_exp_f32_e32 v69, v69
	v_sub_f32_e32 v166, v97, v86
	v_add_f32_e32 v0, 1.0, v69
	v_rcp_f32_e32 v169, v0
	v_mul_f32_e32 v0, 0xbf60028b, v3
	v_exp_f32_e32 v69, v0
	v_add_f32_e32 v0, v34, v70
	v_mul_f32_e64 v3, v0, s68
	v_exp_f32_e32 v3, v3
	v_pk_add_f32 v[72:73], v[168:169], -1.0 op_sel_hi:[1,0]
	v_pk_fma_f32 v[84:85], v[8:9], v[164:165], v[84:85]
	v_pk_fma_f32 v[72:73], v[44:45], v[72:73], 1.0 op_sel_hi:[1,1,0]
	v_add_f32_e32 v3, 1.0, v3
	v_pk_fma_f32 v[76:77], v[4:5], v[80:81], v[76:77]
	v_pk_mul_f32 v[72:73], v[84:85], v[72:73]
	v_rcp_f32_e32 v0, v3
	v_mul_f32_e32 v70, v76, v72
	v_fma_f32 v97, v48, v70, 0
	v_pk_fma_f32 v[86:87], v[10:11], v[166:167], v[86:87]
	v_pk_fma_f32 v[78:79], v[6:7], v[82:83], v[78:79]
	v_mul_f32_e32 v3, v77, v73
	v_fmac_f32_e32 v97, v49, v3
	v_add_f32_e32 v3, v35, v71
	v_mul_f32_e64 v70, v3, s68
	v_exp_f32_e32 v70, v70
	v_add_f32_e32 v71, v38, v74
	v_add_f32_e32 v70, 1.0, v70
	v_mul_f32_e32 v71, 0xbfb8aa3b, v71
	v_exp_f32_e32 v71, v71
	v_rcp_f32_e32 v3, v70
	v_mul_f32_e32 v0, 0xbf60028b, v0
	v_exp_f32_e32 v70, v0
	v_add_f32_e32 v0, 1.0, v71
	v_rcp_f32_e32 v170, v0
	v_add_f32_e32 v71, v39, v75
	v_mul_f32_e32 v71, 0xbfb8aa3b, v71
	v_exp_f32_e32 v71, v71
	s_nop 0
	v_add_f32_e32 v0, 1.0, v71
	v_rcp_f32_e32 v171, v0
	v_pk_mul_f32 v[164:165], v[40:41], v[84:85]
	v_mul_f32_e32 v0, 0xbf60028b, v3
	v_pk_mul_f32 v[84:85], v[164:165], v[164:165]
	v_pk_add_f32 v[74:75], v[170:171], -1.0 op_sel_hi:[1,0]
	v_exp_f32_e32 v71, v0
	v_pk_fma_f32 v[74:75], v[46:47], v[74:75], 1.0 op_sel_hi:[1,1,0]
	v_pk_mul_f32 v[166:167], v[42:43], v[86:87]
	v_pk_mul_f32 v[74:75], v[86:87], v[74:75]
	v_pk_mul_f32 v[86:87], v[166:167], v[166:167]
	v_mul_f32_e32 v0, v78, v74
	v_fmac_f32_e32 v97, v50, v0
	v_add_f32_e32 v0, v84, v85
	v_add_f32_e32 v0, v86, v0
	v_add_f32_e32 v0, v87, v0
	v_mul_f32_e32 v3, v79, v75
	v_fmac_f32_e32 v97, v51, v3
	v_add_f32_dpp v0, v0, v0 quad_perm:[1,0,3,2] row_mask:0xf bank_mask:0xf bound_ctrl:1
	v_pk_fma_f32 v[84:85], v[24:25], v[92:93], v[88:89]
	v_add_f32_dpp v3, v97, v97 quad_perm:[1,0,3,2] row_mask:0xf bank_mask:0xf bound_ctrl:1
	v_add_f32_dpp v0, v0, v0 quad_perm:[2,3,0,1] row_mask:0xf bank_mask:0xf bound_ctrl:1
	v_lshlrev_b32_e32 v90, 16, v109
	v_lshlrev_b32_e32 v94, 16, v111
	v_add_f32_dpp v0, v0, v0 row_half_mirror row_mask:0xf bank_mask:0xf bound_ctrl:1
	v_sub_f32_e32 v94, v94, v90
	v_pk_fma_f32 v[86:87], v[26:27], v[94:95], v[90:91]
	v_add_f32_dpp v0, v0, v0 row_mirror row_mask:0xf bank_mask:0xf bound_ctrl:1
	v_sqrt_f32_e32 v0, v0
	ds_read_b128 v[80:83], v141 offset:39040
	v_xor_b32_e32 v0, 0x80000000, v0
	v_min_f32_e32 v0, 0xab8cbccc, v0
	v_rcp_f32_e32 v88, v0
	s_nop 0
	v_add_f32_dpp v0, v3, v3 quad_perm:[2,3,0,1] row_mask:0xf bank_mask:0xf bound_ctrl:1
	v_pk_mul_f32 v[90:91], v[166:167], v[88:89] op_sel_hi:[1,0]
	s_nop 0
	v_add_f32_dpp v0, v0, v0 row_half_mirror row_mask:0xf bank_mask:0xf bound_ctrl:1
	v_pk_mul_f32 v[88:89], v[164:165], v[88:89] op_sel_hi:[1,0]
	v_pk_mul_f32 v[94:95], v[170:171], v[90:91] neg_lo:[0,1] neg_hi:[0,1]
	v_mov_b32_dpp v3, v0 row_mirror row_mask:0xf bank_mask:0xf bound_ctrl:1
	v_pk_mul_f32 v[92:93], v[168:169], v[88:89] neg_lo:[0,1] neg_hi:[0,1]
	ds_write_b128 v143, v[68:71] offset:49920
	ds_write_b128 v143, v[88:91] offset:54016
	ds_write_b128 v143, v[92:95] offset:58112
	ds_write_b128 v143, v[72:75] offset:62208
	ds_write_b128 v144, v[76:79]
	ds_write_b128 v146, v[84:87]
	s_waitcnt lgkmcnt(6)
	ds_write_b128 v148, v[80:83]
	s_and_saveexec_b64 s[18:19], s[16:17]
	s_cbranch_execz .LBB0_202
	v_add_f32_e32 v0, v0, v3
	ds_write_b32 v152, v0
	s_branch .LBB0_202
